# v55 + grid-sync release: non-leader workgroups poll the top generation word directly (one fewer hop)
# baseline (speedup 1.0000x reference)
.LBB0_111:
	s_or_b64 exec, exec, s[8:9]
	v_cvt_f32_u32_e32 v5, v3
	s_waitcnt vmcnt(0)
	v_readfirstlane_b32 s2, v4
	v_sub_u32_e32 v4, 0, v3
	v_rcp_iflag_f32_e32 v5, v5
	v_add_u32_e32 v6, s2, v0
	v_mul_f32_e32 v5, 0x4f7ffffe, v5
	v_cvt_u32_f32_e32 v5, v5
	v_mul_lo_u32 v0, v4, v5
	v_mul_hi_u32 v0, v5, v0
	v_add_u32_e32 v0, v5, v0
	v_mul_hi_u32 v0, v6, v0
	v_mul_lo_u32 v4, v0, v3
	v_sub_u32_e32 v4, v6, v4
	v_add_u32_e32 v5, 1, v0
	v_cmp_ge_u32_e32 vcc, v4, v3
	s_nop 1
	v_cndmask_b32_e32 v0, v0, v5, vcc
	v_sub_u32_e32 v5, v4, v3
	v_cndmask_b32_e32 v4, v4, v5, vcc
	v_add_u32_e32 v5, 1, v0
	v_cmp_ge_u32_e32 vcc, v4, v3
	v_add_u32_e32 v4, 1, v6
	s_nop 0
	v_cndmask_b32_e32 v0, v0, v5, vcc
	v_mul_lo_u32 v5, v3, v0
	v_add_u32_e32 v3, v5, v3
	v_cmp_ne_u32_e32 vcc, v4, v3
	s_and_saveexec_b64 s[2:3], vcc
	s_xor_b64 s[8:9], exec, s[2:3]
	s_cbranch_execz .LBB0_125
	s_waitcnt lgkmcnt(0)
	s_add_u32 s14, s4, 0x3500
	s_addc_u32 s15, s5, 0
	global_load_dword v2, v1, s[14:15] sc1
	s_waitcnt vmcnt(0)
	v_cmp_eq_u32_e32 vcc, v2, v0
	s_and_saveexec_b64 s[10:11], vcc
	s_cbranch_execz .LBB0_124
	s_mov_b32 s24, 1
	s_mov_b64 s[2:3], 0
	s_branch .LBB0_115

.LBB0_320:
	s_or_b64 exec, exec, s[8:9]
	v_cvt_f32_u32_e32 v5, v3
	s_waitcnt vmcnt(0)
	v_readfirstlane_b32 s2, v4
	v_sub_u32_e32 v4, 0, v3
	v_rcp_iflag_f32_e32 v5, v5
	v_add_u32_e32 v6, s2, v0
	v_mul_f32_e32 v5, 0x4f7ffffe, v5
	v_cvt_u32_f32_e32 v5, v5
	v_mul_lo_u32 v0, v4, v5
	v_mul_hi_u32 v0, v5, v0
	v_add_u32_e32 v0, v5, v0
	v_mul_hi_u32 v0, v6, v0
	v_mul_lo_u32 v4, v0, v3
	v_sub_u32_e32 v4, v6, v4
	v_add_u32_e32 v5, 1, v0
	v_cmp_ge_u32_e32 vcc, v4, v3
	s_nop 1
	v_cndmask_b32_e32 v0, v0, v5, vcc
	v_sub_u32_e32 v5, v4, v3
	v_cndmask_b32_e32 v4, v4, v5, vcc
	v_add_u32_e32 v5, 1, v0
	v_cmp_ge_u32_e32 vcc, v4, v3
	v_add_u32_e32 v4, 1, v6
	s_nop 0
	v_cndmask_b32_e32 v0, v0, v5, vcc
	v_mul_lo_u32 v5, v3, v0
	v_add_u32_e32 v3, v5, v3
	v_cmp_ne_u32_e32 vcc, v4, v3
	s_and_saveexec_b64 s[2:3], vcc
	s_xor_b64 s[8:9], exec, s[2:3]
	s_cbranch_execz .LBB0_334
	s_waitcnt lgkmcnt(0)
	s_add_u32 s16, s4, 0x3500
	s_addc_u32 s17, s5, 0
	global_load_dword v2, v1, s[16:17] sc1
	s_waitcnt vmcnt(0)
	v_cmp_eq_u32_e32 vcc, v2, v0
	s_and_saveexec_b64 s[10:11], vcc
	s_cbranch_execz .LBB0_333
	s_mov_b32 s26, 1
	s_mov_b64 s[2:3], 0
	s_branch .LBB0_324
